# v55 plus grid barrier flat release: non-leader workgroups poll the cross-XCD release generation word instead of their XCD's own generation word (one fewer store+poll hop per barrier)
# speedup vs baseline: 1.0013x; 1.0013x over previous
; __device__ __forceinline__ unsigned xb_ld(unsigned* p)              { return __hip_atomic_load(p, __ATOMIC_RELAXED, __HIP_MEMORY_SCOPE_AGENT); }
; __device__ __forceinline__ unsigned xb_add(unsigned* p, unsigned v) { return __hip_atomic_fetch_add(p, v, __ATOMIC_RELAXED, __HIP_MEMORY_SCOPE_AGENT); }
; #define XB_SPIN(cond, bar) do { unsigned _sp = 0; while (cond) { __builtin_amdgcn_s_sleep(1); \
;     if ((++_sp & 255u) == 0u) { if (xb_ld(&(bar)[XB_TMO])) break; if (_sp > XB_SPIN_CAP) { atomicAdd(&(bar)[XB_TMO], 1u); break; } } } } while (0)
; __device__ __forceinline__ void xcd_barrier(const XcdBarrier& b) {
;     ...
;         const unsigned old = xb_add(&bar[XB_XSUB(b.x)], 1u);
;         const unsigned gen = old / nloc;
;         if (old + 1u == (gen + 1u) * nloc) {
;             __builtin_amdgcn_fence(__ATOMIC_RELEASE, "agent");
;             asm volatile("s_waitcnt vmcnt(0)" ::: "memory");
;             const unsigned og = xb_add(&bar[XB_TOP], 1u);
;             const unsigned tg = og / nx;
;             if (og + 1u == (tg + 1u) * nx) xb_add(&bar[XB_TOPGEN], 1u);
;             else XB_SPIN(xb_ld(&bar[XB_TOPGEN]) == tg, bar);
;             __builtin_amdgcn_fence(__ATOMIC_ACQUIRE, "agent");
;             xb_add(&bar[XB_XGEN(b.x)], 1u);
;             asm volatile("s_waitcnt vmcnt(0)" ::: "memory");
;         } else {
;             XB_SPIN(xb_ld(&bar[XB_XGEN(b.x)]) == gen, bar);
.LBB0_514:
	s_or_b64 exec, exec, s[4:5]
	v_cvt_f32_u32_e32 v6, v4
	s_waitcnt vmcnt(0)
	v_readfirstlane_b32 s2, v5
	v_sub_u32_e32 v5, 0, v4
	v_rcp_iflag_f32_e32 v6, v6
	v_add_u32_e32 v7, s2, v1
	v_mul_f32_e32 v6, 0x4f7ffffe, v6
	v_cvt_u32_f32_e32 v6, v6
	v_mul_lo_u32 v1, v5, v6
	v_mul_hi_u32 v1, v6, v1
	v_add_u32_e32 v1, v6, v1
	v_mul_hi_u32 v1, v7, v1
	v_mul_lo_u32 v5, v1, v4
	v_sub_u32_e32 v5, v7, v5
	v_add_u32_e32 v6, 1, v1
	v_cmp_ge_u32_e32 vcc, v5, v4
	s_nop 1
	v_cndmask_b32_e32 v1, v1, v6, vcc
	v_sub_u32_e32 v6, v5, v4
	v_cndmask_b32_e32 v5, v5, v6, vcc
	v_add_u32_e32 v6, 1, v1
	v_cmp_ge_u32_e32 vcc, v5, v4
	v_add_u32_e32 v5, 1, v7
	s_nop 0
	v_cndmask_b32_e32 v1, v1, v6, vcc
	v_mul_lo_u32 v6, v4, v1
	v_add_u32_e32 v4, v6, v4
	v_cmp_ne_u32_e32 vcc, v5, v4
	s_and_saveexec_b64 s[4:5], vcc
	s_xor_b64 s[4:5], exec, s[4:5]
	s_cbranch_execz .LBB0_531
	v_readlane_b32 s6, v250, 50
	v_readlane_b32 s7, v250, 51
	s_waitcnt lgkmcnt(0)
	s_nop 3
	global_load_dword v2, v3, s[6:7] sc1
	s_waitcnt vmcnt(0)
	v_cmp_eq_u32_e32 vcc, v2, v1
	s_and_saveexec_b64 s[6:7], vcc
	s_cbranch_execz .LBB0_530
	s_mov_b32 s2, 1
	s_mov_b64 s[8:9], 0
	s_branch .LBB0_518

; __device__ __forceinline__ unsigned xb_ld(unsigned* p)              { return __hip_atomic_load(p, __ATOMIC_RELAXED, __HIP_MEMORY_SCOPE_AGENT); }
; __device__ __forceinline__ unsigned xb_add(unsigned* p, unsigned v) { return __hip_atomic_fetch_add(p, v, __ATOMIC_RELAXED, __HIP_MEMORY_SCOPE_AGENT); }
; #define XB_SPIN(cond, bar) do { unsigned _sp = 0; while (cond) { __builtin_amdgcn_s_sleep(1); \
;     if ((++_sp & 255u) == 0u) { if (xb_ld(&(bar)[XB_TMO])) break; if (_sp > XB_SPIN_CAP) { atomicAdd(&(bar)[XB_TMO], 1u); break; } } } } while (0)
; __device__ __forceinline__ void xcd_barrier(const XcdBarrier& b) {
;     ...
;         const unsigned old = xb_add(&bar[XB_XSUB(b.x)], 1u);
;         const unsigned gen = old / nloc;
;         if (old + 1u == (gen + 1u) * nloc) {
;             __builtin_amdgcn_fence(__ATOMIC_RELEASE, "agent");
;             asm volatile("s_waitcnt vmcnt(0)" ::: "memory");
;             const unsigned og = xb_add(&bar[XB_TOP], 1u);
;             const unsigned tg = og / nx;
;             if (og + 1u == (tg + 1u) * nx) xb_add(&bar[XB_TOPGEN], 1u);
;             else XB_SPIN(xb_ld(&bar[XB_TOPGEN]) == tg, bar);
;             __builtin_amdgcn_fence(__ATOMIC_ACQUIRE, "agent");
;             xb_add(&bar[XB_XGEN(b.x)], 1u);
;             asm volatile("s_waitcnt vmcnt(0)" ::: "memory");
;         } else {
;             XB_SPIN(xb_ld(&bar[XB_XGEN(b.x)]) == gen, bar);
.LBB0_1016:
	s_or_b64 exec, exec, s[4:5]
	v_cvt_f32_u32_e32 v12, v8
	s_waitcnt vmcnt(0)
	v_readfirstlane_b32 s2, v10
	v_sub_u32_e32 v10, 0, v8
	v_rcp_iflag_f32_e32 v12, v12
	v_add_u32_e32 v14, s2, v2
	v_mul_f32_e32 v12, 0x4f7ffffe, v12
	v_cvt_u32_f32_e32 v12, v12
	v_mul_lo_u32 v2, v10, v12
	v_mul_hi_u32 v2, v12, v2
	v_add_u32_e32 v2, v12, v2
	v_mul_hi_u32 v2, v14, v2
	v_mul_lo_u32 v10, v2, v8
	v_sub_u32_e32 v10, v14, v10
	v_add_u32_e32 v12, 1, v2
	v_cmp_ge_u32_e32 vcc, v10, v8
	s_nop 1
	v_cndmask_b32_e32 v2, v2, v12, vcc
	v_sub_u32_e32 v12, v10, v8
	v_cndmask_b32_e32 v10, v10, v12, vcc
	v_add_u32_e32 v12, 1, v2
	v_cmp_ge_u32_e32 vcc, v10, v8
	v_add_u32_e32 v10, 1, v14
	s_nop 0
	v_cndmask_b32_e32 v2, v2, v12, vcc
	v_mul_lo_u32 v12, v8, v2
	v_add_u32_e32 v8, v12, v8
	v_cmp_ne_u32_e32 vcc, v10, v8
	s_and_saveexec_b64 s[4:5], vcc
	s_xor_b64 s[4:5], exec, s[4:5]
	s_cbranch_execz .LBB0_1030
	v_readlane_b32 s6, v250, 50
	v_readlane_b32 s7, v250, 51
	s_waitcnt lgkmcnt(0)
	s_nop 3
	global_load_dword v5, v3, s[6:7] sc1
	s_waitcnt vmcnt(0)
	v_cmp_eq_u32_e32 vcc, v5, v2
	s_and_saveexec_b64 s[6:7], vcc
	s_cbranch_execz .LBB0_1029
	s_mov_b32 s2, 1
	s_mov_b64 s[8:9], 0
	s_branch .LBB0_1020
